# G1 in-proj GEMM epilogue: the 8 rope cos/sin loads of each half issued together with one wait (replaces serial load-wait rounds and the earlier L1 prefetch)
# speedup vs baseline: 1.0321x; 1.0166x over previous
.LBB0_494:
	s_or_b32 s10, s9, s90
	s_cmp_ge_i32 s10, s52
	s_cselect_b64 s[12:13], -1, 0
	s_cmp_lt_i32 s10, s57
	s_cselect_b64 s[14:15], -1, 0
	s_and_b64 s[12:13], s[12:13], s[14:15]
	s_and_b64 s[12:13], s[12:13], exec
	s_cselect_b32 s9, 2, 0
	s_cmp_ge_i32 s10, s53
	s_cselect_b32 s11, s9, 1
	s_or_b32 s9, s10, 0x80
	s_cmp_ge_i32 s9, s52
	s_cselect_b64 s[12:13], -1, 0
	s_cmp_lt_i32 s9, s57
	s_cselect_b64 s[14:15], -1, 0
	s_and_b64 s[12:13], s[12:13], s[14:15]
	s_and_b64 s[12:13], s[12:13], exec
	s_cselect_b32 s12, 2, 0
	s_cmp_ge_i32 s9, s53
	s_cselect_b32 s12, s12, 1
	s_or_b32 s13, s11, s12
	s_cmp_eq_u32 s13, 1
	s_cselect_b64 s[64:65], -1, 0
	v_lshl_add_u32 v222, s8, 8, v228
	s_and_b64 s[8:9], s[64:65], exec
	s_cselect_b32 s8, s36, 0
	v_or_b32_e32 v0, s8, v231
	s_cselect_b32 s9, s68, s35
	s_cselect_b32 s8, s33, s34
	v_lshlrev_b32_e32 v0, 2, v0
	s_cselect_b32 s15, s70, s61
	s_cselect_b32 s14, s69, s60
	s_cmp_lg_u32 s13, 0
	v_lshl_add_u64 v[220:221], s[8:9], 0, v[0:1]
	s_cselect_b64 s[8:9], -1, 0
	s_cmp_eq_u32 s13, 0
	v_lshl_add_u64 v[226:227], s[14:15], 0, v[0:1]
	v_cndmask_b32_e64 v0, 0, 1, s[8:9]
	v_or_b32_e32 v234, 16, v222
	v_or_b32_e32 v233, 32, v222
	v_or_b32_e32 v223, 48, v222
	s_andn2_b64 vcc, exec, s[8:9]
	v_cmp_ne_u32_e64 s[16:17], 1, v0
	s_cbranch_vccnz .Lg1h1_norope
	s_and_b64 vcc, s[64:65], exec
	v_and_b32_e32 v0, 0x7cf, v222
	s_cselect_b32 s8, 5, 4
	v_lshlrev_b32_e32 v0, s8, v0
	v_lshlrev_b32_e32 v0, 2, v0
	s_lshl_b32 s100, 64, s8
	s_mov_b32 s101, 0
	v_lshl_add_u64 v[58:59], v[220:221], 0, v[0:1]
	v_lshl_add_u64 v[60:61], v[226:227], 0, v[0:1]
	global_load_dwordx4 v[2:5], v[58:59], off
	global_load_dwordx4 v[186:189], v[60:61], off
	v_lshl_add_u64 v[58:59], v[58:59], 0, s[100:101]
	v_lshl_add_u64 v[60:61], v[60:61], 0, s[100:101]
	global_load_dwordx4 v[6:9], v[58:59], off
	global_load_dwordx4 v[174:177], v[60:61], off
	v_lshl_add_u64 v[58:59], v[58:59], 0, s[100:101]
	v_lshl_add_u64 v[60:61], v[60:61], 0, s[100:101]
	global_load_dwordx4 v[10:13], v[58:59], off
	global_load_dwordx4 v[162:165], v[60:61], off
	v_lshl_add_u64 v[58:59], v[58:59], 0, s[100:101]
	v_lshl_add_u64 v[60:61], v[60:61], 0, s[100:101]
	global_load_dwordx4 v[14:17], v[58:59], off
	global_load_dwordx4 v[150:153], v[60:61], off
	s_branch .Lg1h1_wait

.Lg1h1_wait:
	s_waitcnt vmcnt(0)
.LBB0_504:
	s_cmp_gt_i32 s86, -1
	v_mad_i64_i32 v[58:59], s[8:9], v222, s76, 0
	s_cselect_b64 s[14:15], -1, 0
	s_cmp_lt_i32 s86, 0
	s_cbranch_scc1 .LBB0_508
	v_mul_f32_e32 v0, v203, v203
	v_mul_f32_e32 v60, v205, v205
	v_fmac_f32_e32 v0, v202, v202
	v_fmac_f32_e32 v60, v204, v204
	v_add_f32_e32 v0, v0, v60
	v_mul_f32_e32 v60, v199, v199
	v_fmac_f32_e32 v60, v198, v198
	v_add_f32_e32 v0, v0, v60
	v_mul_f32_e32 v60, v201, v201
	v_fmac_f32_e32 v60, v200, v200
	v_add_f32_e32 v0, v60, v0
	v_mov_b32_e32 v60, v0
	s_nop 1
	v_permlane16_swap_b32_e32 v0, v60
	v_add_f32_e32 v0, v0, v60
	v_mov_b32_e32 v60, v0
	s_nop 1
	v_permlane32_swap_b32_e32 v0, v60
	s_and_saveexec_b64 s[8:9], s[4:5]
	s_cbranch_execz .LBB0_507
	v_readlane_b32 s48, v254, 25
	v_readlane_b32 s49, v254, 26
	v_add_f32_e32 v0, v0, v60
	s_nop 0
	v_lshl_add_u64 v[60:61], s[48:49], 0, v[58:59]
	v_lshl_add_u64 v[60:61], s[86:87], 2, v[60:61]
	global_store_dword v[60:61], v0, off

.LBB0_536:
	v_pk_mul_f32 v[58:59], v[128:129], v[152:153]
	v_pk_mul_f32 v[134:135], v[126:127], v[150:151]
	v_pk_mul_f32 v[136:137], v[128:129], v[16:17]
	v_pk_mul_f32 v[138:139], v[126:127], v[14:15]
	v_pk_fma_f32 v[58:59], v[132:133], v[16:17], v[58:59] neg_lo:[0,0,1] neg_hi:[0,0,1]
	v_pk_fma_f32 v[134:135], v[130:131], v[14:15], v[134:135] neg_lo:[0,0,1] neg_hi:[0,0,1]
	v_pk_fma_f32 v[136:137], v[132:133], v[152:153], v[136:137]
	v_pk_fma_f32 v[138:139], v[130:131], v[150:151], v[138:139]
	v_cndmask_b32_e64 v0, v59, v133, s[10:11]
	v_cndmask_b32_e64 v58, v58, v132, s[10:11]
	v_cndmask_b32_e64 v59, v135, v131, s[10:11]
	v_cndmask_b32_e64 v130, v134, v130, s[10:11]
	v_cndmask_b32_e64 v129, v137, v129, s[10:11]
	v_cndmask_b32_e64 v131, v136, v128, s[10:11]
	v_cndmask_b32_e64 v128, v139, v127, s[10:11]
	v_cndmask_b32_e64 v132, v138, v126, s[10:11]
	v_cvt_pk_bf16_f32 v126, v130, v59
	v_cvt_pk_bf16_f32 v127, v58, v0
	v_cvt_pk_bf16_f32 v128, v132, v128
	v_cvt_pk_bf16_f32 v129, v131, v129
	global_store_dwordx4 v[60:61], v[126:129], off offset:256
	s_and_b64 vcc, exec, s[16:17]
	s_nop 0
	v_add_u32_e32 v126, 0x80, v222
	v_add_u32_e32 v35, 0x90, v222
	v_add_u32_e32 v34, 0xa0, v222
	v_add_u32_e32 v22, 0xb0, v222
	s_cbranch_vccnz .LBB0_544
	s_and_b64 vcc, s[64:65], exec
	v_and_b32_e32 v0, 0x7cf, v126
	s_cselect_b32 s39, 5, 4
	v_lshlrev_b32_e32 v0, s39, v0
	v_lshlrev_b32_e32 v0, 2, v0
	s_lshl_b32 s100, 64, s39
	s_mov_b32 s101, 0
	v_lshl_add_u64 v[58:59], v[220:221], 0, v[0:1]
	v_lshl_add_u64 v[60:61], v[226:227], 0, v[0:1]
	global_load_dwordx4 v[2:5], v[58:59], off
	global_load_dwordx4 v[186:189], v[60:61], off
	v_lshl_add_u64 v[58:59], v[58:59], 0, s[100:101]
	v_lshl_add_u64 v[60:61], v[60:61], 0, s[100:101]
	global_load_dwordx4 v[6:9], v[58:59], off
	global_load_dwordx4 v[174:177], v[60:61], off
	v_lshl_add_u64 v[58:59], v[58:59], 0, s[100:101]
	v_lshl_add_u64 v[60:61], v[60:61], 0, s[100:101]
	global_load_dwordx4 v[10:13], v[58:59], off
	global_load_dwordx4 v[162:165], v[60:61], off
	v_lshl_add_u64 v[58:59], v[58:59], 0, s[100:101]
	v_lshl_add_u64 v[60:61], v[60:61], 0, s[100:101]
	global_load_dwordx4 v[14:17], v[58:59], off
	global_load_dwordx4 v[150:153], v[60:61], off
	s_waitcnt vmcnt(0)
